# final RMSNorm phase: row loads issued together, gains kept in registers, one wait per row instead of 13 serialized round trips
# speedup vs baseline: 1.0062x; 1.0062x over previous
; __device__ __forceinline__ f32x4 bf4lo(u32x4 r) { return (f32x4){bflo(r.x), bfhi(r.x), bflo(r.y), bfhi(r.y)}; }
; __device__ __forceinline__ f32x4 bf4hi(u32x4 r) { return (f32x4){bflo(r.z), bfhi(r.z), bflo(r.w), bfhi(r.w)}; }
; __device__ __forceinline__ void final_norm_phase(const Ctx& C, const bf16_t* xn, const float* hss, const float* gfin, float* outf) {
;     const int gw = C.wg * NWAVES + C.wave, NGW = C.G * NWAVES;
;     for (int m = gw; m < M_TOK; m += NGW) {
;         float s = C.lane < 32 ? hss[(size_t)m * 64 + C.lane] : 0.f;
;         const float rs = 1.0f / sqrtf(wave_sum(s) * (1.0f / DM) + EPS);
;         const u32x4* xr = (const u32x4*)(xn + (size_t)m * DM) + C.lane;
;         f32x4* o = (f32x4*)(outf + (size_t)m * DM); const f32x4* g4 = (const f32x4*)gfin;
; #pragma unroll
;         for (int j = 0; j < 4; ++j) { const u32x4 r = xr[64 * j]; const int c4 = 2 * (C.lane + 64 * j);
;             o[c4] = pg8::bf4lo(r) * rs * g4[c4]; o[c4 + 1] = pg8::bf4hi(r) * rs * g4[c4 + 1]; }
;     }
.LBB0_15:
	v_mov_b32_e32 v250, v205
	s_mov_b64 s[22:23], -1
	v_readfirstlane_b32 s0, v250
	s_ashr_i32 s73, s0, 6
	v_and_b32_e32 v204, 63, v250
	v_writelane_b32 v254, s0, 61
	v_readlane_b32 s0, v252, 14
	v_readlane_b32 s1, v252, 15
	s_load_dword s0, s[0:1], 0x0
	s_mov_b64 s[26:27], 0
	s_waitcnt lgkmcnt(0)
	v_writelane_b32 v254, s0, 63
	v_readlane_b32 s0, v252, 3
	v_readlane_b32 s1, v252, 4
	s_cmp_lt_i32 s0, 25
	s_mov_b64 s[0:1], 0
	s_cbranch_scc1 .LBB0_22
	v_readlane_b32 s0, v252, 3
	v_readlane_b32 s1, v252, 4
	s_cmp_eq_u32 s0, 25
	s_mov_b64 s[0:1], -1
	s_cbranch_scc0 .LBB0_26
	v_readlane_b32 s0, v254, 30
	s_nop 1
	v_mov_b32_e32 v0, s0
	ds_read_b64 v[0:1], v0
	v_readlane_b32 s0, v252, 16
	s_add_i32 s40, s73, s0
	s_cmpk_gt_i32 s40, 0x7fff
	s_waitcnt lgkmcnt(0)
	v_readfirstlane_b32 s1, v1
	v_readfirstlane_b32 s0, v0
	s_cbranch_scc1 .LBB0_25
	v_cmp_lt_i32_e32 vcc, v240, v243
	v_lshlrev_b32_e32 v64, 5, v204
	v_readlane_b32 s22, v254, 63
	v_cndmask_b32_e32 v0, v242, v240, vcc
	v_cmp_lt_i32_e32 vcc, v251, v243
	v_lshlrev_b32_e32 v17, 2, v0
	v_or_b32_e32 v2, 0x1000, v64
	v_cndmask_b32_e32 v0, v242, v251, vcc
	v_lshlrev_b32_e32 v20, 2, v0
	v_xor_b32_e32 v0, 4, v242
	v_cmp_lt_i32_e32 vcc, v0, v243
	v_mov_b32_e32 v3, v65
	v_or_b32_e32 v4, 0x1010, v64
	v_cndmask_b32_e32 v0, v242, v0, vcc
	v_lshlrev_b32_e32 v21, 2, v0
	v_xor_b32_e32 v0, 8, v242
	v_cmp_lt_i32_e32 vcc, v0, v243
	v_mov_b32_e32 v5, v65
	v_or_b32_e32 v6, 0x1800, v64
	v_cndmask_b32_e32 v0, v242, v0, vcc
	v_cmp_lt_i32_e32 vcc, v248, v243
	v_lshlrev_b32_e32 v22, 2, v0
	v_mov_b32_e32 v7, v65
	v_cndmask_b32_e32 v0, v242, v248, vcc
	v_cmp_lt_i32_e32 vcc, v249, v243
	v_lshlrev_b32_e32 v23, 2, v0
	v_or_b32_e32 v8, 0x1810, v64
	v_cndmask_b32_e32 v0, v242, v249, vcc
	v_mov_b32_e32 v9, v65
	s_ashr_i32 s41, s40, 31
	s_lshl_b32 s42, s22, 3
	v_lshlrev_b32_e32 v24, 2, v0
	v_lshl_add_u64 v[0:1], s[0:1], 0, v[64:65]
	v_lshl_add_u64 v[2:3], s[0:1], 0, v[2:3]
	v_lshl_add_u64 v[4:5], s[0:1], 0, v[4:5]
	v_lshl_add_u64 v[6:7], s[0:1], 0, v[6:7]
	v_lshl_add_u64 v[8:9], s[0:1], 0, v[8:9]
	s_lshl_b64 s[0:1], s[40:41], 8
	s_add_u32 s0, s0, 0x38800000
	s_addc_u32 s1, s1, 0
	v_lshl_or_b32 v10, v204, 2, s0
	v_mov_b32_e32 v11, s1
	s_ashr_i32 s43, s42, 31
	s_lshl_b64 s[0:1], s[40:41], 12
	s_lshl_b64 s[44:45], s[42:43], 8
	v_lshl_or_b32 v12, v204, 4, s0
	v_mov_b32_e32 v13, s1
	s_lshl_b64 s[46:47], s[42:43], 12
	s_lshl_b64 s[0:1], s[40:41], 13
	v_readlane_b32 s22, v254, 17
	s_add_u32 s0, s22, s0
	v_readlane_b32 s22, v254, 18
	s_addc_u32 s1, s22, s1
	v_cmp_gt_u32_e64 s[38:39], 32, v204
	v_lshl_add_u64 v[14:15], s[0:1], 0, v[64:65]
	s_lshl_b64 s[54:55], s[42:43], 13
	global_load_dwordx4 v[100:103], v[0:1], off
	global_load_dwordx4 v[104:107], v[0:1], off offset:16
	global_load_dwordx4 v[108:111], v[0:1], off offset:2048
	global_load_dwordx4 v[112:115], v[0:1], off offset:2064
	global_load_dwordx4 v[116:119], v[2:3], off
	global_load_dwordx4 v[120:123], v[4:5], off
	global_load_dwordx4 v[124:127], v[6:7], off
	global_load_dwordx4 v[128:131], v[8:9], off
	s_waitcnt vmcnt(0)
	s_branch .LBB0_20
; __device__ __forceinline__ f32x4 bf4lo(u32x4 r) { return (f32x4){bflo(r.x), bfhi(r.x), bflo(r.y), bfhi(r.y)}; }
; __device__ __forceinline__ f32x4 bf4hi(u32x4 r) { return (f32x4){bflo(r.z), bfhi(r.z), bflo(r.w), bfhi(r.w)}; }
; __device__ __forceinline__ void final_norm_phase(const Ctx& C, const bf16_t* xn, const float* hss, const float* gfin, float* outf) {
;     ...
;     for (int m = gw; m < M_TOK; m += NGW) {
;         float s = C.lane < 32 ? hss[(size_t)m * 64 + C.lane] : 0.f;
;         const float rs = 1.0f / sqrtf(wave_sum(s) * (1.0f / DM) + EPS);
;         const u32x4* xr = (const u32x4*)(xn + (size_t)m * DM) + C.lane;
;         f32x4* o = (f32x4*)(outf + (size_t)m * DM); const f32x4* g4 = (const f32x4*)gfin;
; #pragma unroll
;         for (int j = 0; j < 4; ++j) { const u32x4 r = xr[64 * j]; const int c4 = 2 * (C.lane + 64 * j);
;             o[c4] = pg8::bf4lo(r) * rs * g4[c4]; o[c4 + 1] = pg8::bf4hi(r) * rs * g4[c4 + 1]; }
;     }
.LBB0_19:
	s_or_b64 exec, exec, s[0:1]
	v_lshl_add_u64 v[18:19], s[66:67], 0, v[12:13]
	s_mov_b32 s0, 0x18800000
	v_add_co_u32_e32 v18, vcc, s0, v18
	v_lshl_add_u64 v[12:13], v[12:13], 0, s[46:47]
	s_nop 0
	v_addc_co_u32_e32 v19, vcc, 0, v19, vcc
	global_load_dwordx4 v[132:135], v[18:19], off
	global_load_dwordx4 v[136:139], v[18:19], off offset:1024
	global_load_dwordx4 v[140:143], v[18:19], off offset:2048
	global_load_dwordx4 v[144:147], v[18:19], off offset:3072
	s_waitcnt vmcnt(4)
	ds_bpermute_b32 v18, v17, v16
	s_mov_b32 s0, 0xf800000
	s_add_i32 s40, s40, s42
	v_lshl_add_u64 v[10:11], v[10:11], 0, s[44:45]
	s_cmpk_gt_i32 s40, 0x7fff
	s_waitcnt lgkmcnt(0)
	v_add_f32_e32 v16, v16, v18
	ds_bpermute_b32 v18, v20, v16
	s_waitcnt lgkmcnt(0)
	v_add_f32_e32 v16, v16, v18
	ds_bpermute_b32 v18, v21, v16
	s_waitcnt lgkmcnt(0)
	v_add_f32_e32 v16, v16, v18
	ds_bpermute_b32 v18, v22, v16
	s_waitcnt lgkmcnt(0)
	v_add_f32_e32 v16, v16, v18
	ds_bpermute_b32 v18, v23, v16
	s_waitcnt lgkmcnt(0)
	v_add_f32_e32 v16, v16, v18
	ds_bpermute_b32 v18, v24, v16
	s_waitcnt lgkmcnt(0)
	v_add_f32_e32 v16, v16, v18
	v_fmamk_f32 v16, v16, 0x3a000000, v238
	v_cmp_gt_f32_e32 vcc, s0, v16
	v_mul_f32_e32 v18, 0x4f800000, v16
	s_nop 0
	v_cndmask_b32_e32 v16, v16, v18, vcc
	v_sqrt_f32_e32 v18, v16
	s_nop 0
	v_add_u32_e32 v19, -1, v18
	v_fma_f32 v25, -v19, v18, v16
	v_cmp_ge_f32_e64 s[0:1], 0, v25
	v_add_u32_e32 v25, 1, v18
	s_nop 0
	v_cndmask_b32_e64 v19, v18, v19, s[0:1]
	v_fma_f32 v18, -v25, v18, v16
	v_cmp_lt_f32_e64 s[0:1], 0, v18
	s_nop 1
	v_cndmask_b32_e64 v18, v19, v25, s[0:1]
	v_mul_f32_e32 v19, 0x37800000, v18
	v_cndmask_b32_e32 v18, v18, v19, vcc
	v_cmp_class_f32_e32 vcc, v16, v239
	s_nop 1
	v_cndmask_b32_e32 v16, v18, v16, vcc
	v_div_scale_f32 v18, s[0:1], v16, v16, 1.0
	v_rcp_f32_e32 v19, v18
	s_nop 0
	v_fma_f32 v25, -v18, v19, 1.0
	v_fmac_f32_e32 v19, v25, v19
	v_div_scale_f32 v25, vcc, 1.0, v16, 1.0
	v_mul_f32_e32 v26, v25, v19
	v_fma_f32 v27, -v18, v26, v25
	v_fmac_f32_e32 v26, v27, v19
	v_fma_f32 v18, -v18, v26, v25
	v_div_fmas_f32 v18, v18, v19, v26
	v_div_fixup_f32 v16, v18, v16, 1.0
	s_waitcnt vmcnt(0)
	v_lshlrev_b32_e32 v30, 16, v132
	v_and_b32_e32 v31, 0xffff0000, v132
	v_lshlrev_b32_e32 v32, 16, v133
	v_and_b32_e32 v33, 0xffff0000, v133
	v_pk_mul_f32 v[30:31], v[16:17], v[30:31] op_sel_hi:[0,1]
	v_pk_mul_f32 v[32:33], v[16:17], v[32:33] op_sel_hi:[0,1]
	v_pk_mul_f32 v[30:31], v[100:101], v[30:31]
	v_pk_mul_f32 v[32:33], v[102:103], v[32:33]
	global_store_dwordx4 v[14:15], v[30:33], off offset:-4096
	v_lshlrev_b32_e32 v34, 16, v134
	v_and_b32_e32 v35, 0xffff0000, v134
	v_lshlrev_b32_e32 v36, 16, v135
	v_and_b32_e32 v37, 0xffff0000, v135
	v_pk_mul_f32 v[34:35], v[16:17], v[34:35] op_sel_hi:[0,1]
	v_pk_mul_f32 v[36:37], v[16:17], v[36:37] op_sel_hi:[0,1]
	v_pk_mul_f32 v[34:35], v[104:105], v[34:35]
	v_pk_mul_f32 v[36:37], v[106:107], v[36:37]
	global_store_dwordx4 v[14:15], v[34:37], off offset:-4080
	v_lshlrev_b32_e32 v30, 16, v136
	v_and_b32_e32 v31, 0xffff0000, v136
	v_lshlrev_b32_e32 v32, 16, v137
	v_and_b32_e32 v33, 0xffff0000, v137
	v_pk_mul_f32 v[30:31], v[16:17], v[30:31] op_sel_hi:[0,1]
	v_pk_mul_f32 v[32:33], v[16:17], v[32:33] op_sel_hi:[0,1]
	v_pk_mul_f32 v[30:31], v[108:109], v[30:31]
	v_pk_mul_f32 v[32:33], v[110:111], v[32:33]
	global_store_dwordx4 v[14:15], v[30:33], off offset:-2048
	v_lshlrev_b32_e32 v34, 16, v138
	v_and_b32_e32 v35, 0xffff0000, v138
	v_lshlrev_b32_e32 v36, 16, v139
	v_and_b32_e32 v37, 0xffff0000, v139
	v_pk_mul_f32 v[34:35], v[16:17], v[34:35] op_sel_hi:[0,1]
	v_pk_mul_f32 v[36:37], v[16:17], v[36:37] op_sel_hi:[0,1]
	v_pk_mul_f32 v[34:35], v[112:113], v[34:35]
	v_pk_mul_f32 v[36:37], v[114:115], v[36:37]
	global_store_dwordx4 v[14:15], v[34:37], off offset:-2032
	v_lshlrev_b32_e32 v30, 16, v140
	v_and_b32_e32 v31, 0xffff0000, v140
	v_lshlrev_b32_e32 v32, 16, v141
	v_and_b32_e32 v33, 0xffff0000, v141
	v_pk_mul_f32 v[30:31], v[16:17], v[30:31] op_sel_hi:[0,1]
	v_pk_mul_f32 v[32:33], v[16:17], v[32:33] op_sel_hi:[0,1]
	v_pk_mul_f32 v[30:31], v[116:117], v[30:31]
	v_pk_mul_f32 v[32:33], v[118:119], v[32:33]
	global_store_dwordx4 v[14:15], v[30:33], off
	v_lshlrev_b32_e32 v34, 16, v142
	v_and_b32_e32 v35, 0xffff0000, v142
	v_lshlrev_b32_e32 v36, 16, v143
	v_and_b32_e32 v37, 0xffff0000, v143
	v_pk_mul_f32 v[34:35], v[16:17], v[34:35] op_sel_hi:[0,1]
	v_pk_mul_f32 v[36:37], v[16:17], v[36:37] op_sel_hi:[0,1]
	v_pk_mul_f32 v[34:35], v[120:121], v[34:35]
	v_pk_mul_f32 v[36:37], v[122:123], v[36:37]
	global_store_dwordx4 v[14:15], v[34:37], off offset:16
	v_lshlrev_b32_e32 v30, 16, v144
	v_and_b32_e32 v31, 0xffff0000, v144
	v_lshlrev_b32_e32 v32, 16, v145
	v_and_b32_e32 v33, 0xffff0000, v145
	v_pk_mul_f32 v[30:31], v[16:17], v[30:31] op_sel_hi:[0,1]
	v_pk_mul_f32 v[32:33], v[16:17], v[32:33] op_sel_hi:[0,1]
	v_pk_mul_f32 v[30:31], v[124:125], v[30:31]
	v_pk_mul_f32 v[32:33], v[126:127], v[32:33]
	global_store_dwordx4 v[14:15], v[30:33], off offset:2048
	v_lshlrev_b32_e32 v34, 16, v146
	v_and_b32_e32 v35, 0xffff0000, v146
	v_lshlrev_b32_e32 v36, 16, v147
	v_and_b32_e32 v37, 0xffff0000, v147
	v_pk_mul_f32 v[34:35], v[16:17], v[34:35] op_sel_hi:[0,1]
	v_pk_mul_f32 v[36:37], v[16:17], v[36:37] op_sel_hi:[0,1]
	v_pk_mul_f32 v[34:35], v[128:129], v[34:35]
	v_pk_mul_f32 v[36:37], v[130:131], v[36:37]
	global_store_dwordx4 v[14:15], v[34:37], off offset:2064
	v_lshl_add_u64 v[14:15], v[14:15], 0, s[54:55]
	s_cbranch_scc1 .LBB0_25
